# clean_plus_prologue_ktile1_hoist
# baseline (speedup 1.0000x reference)
.LBB0_210:
	s_and_b32 s5, s5, 3
	s_add_i32 m0, s66, 0x18000
	v_lshl_add_u64 v[8:9], v[8:9], 0, s[82:83]
	s_lshl_b32 s70, s12, 6
	s_lshl_b32 s8, s12, 13
	s_lshl_b32 s13, s5, 5
	s_lshl_b32 s9, s5, 12
	global_load_lds_dwordx4 v[8:9], off
	v_lshl_add_u64 v[6:7], v[6:7], 0, s[82:83]
	s_add_i32 m0, s66, 0x1a000
	s_add_i32 s71, s66, 0x8000
	s_add_i32 s74, s66, 0xa000
	global_load_lds_dwordx4 v[6:7], off
	v_lshl_add_u64 v[2:3], v[2:3], 0, s[82:83]
	s_mov_b32 m0, s71
	s_add_u32 s6, s50, 0x40080
	global_load_lds_dwordx4 v[2:3], off
	v_lshl_add_u64 v[2:3], v[4:5], 0, s[82:83]
	s_mov_b32 m0, s74
	s_addc_u32 s7, s51, 0
	global_load_lds_dwordx4 v[2:3], off
	s_add_i32 m0, s66, 0x1c000
	v_lshl_add_u64 v[2:3], s[6:7], 0, v[140:141]
	global_load_lds_dwordx4 v[2:3], off
	v_lshl_add_u64 v[2:3], s[6:7], 0, v[144:145]
	s_add_i32 m0, s66, 0x1e000
	s_cmpk_lt_u32 s4, 0x100
	global_load_lds_dwordx4 v[2:3], off
	s_waitcnt vmcnt(8)
	s_barrier
	s_cselect_b64 s[34:35], -1, 0
	s_cmp_eq_u32 s5, 0
	s_cselect_b64 s[4:5], -1, 0
	s_lshl_b32 s12, s12, 8
	v_and_b32_e32 v2, 15, v0
	v_bfe_u32 v0, v0, 4, 2
	s_add_i32 s12, s12, 0
	v_lshlrev_b32_e32 v3, 4, v0
	s_add_i32 s12, s12, 0x20400
	v_lshlrev_b32_e32 v146, 3, v0
	v_lshl_or_b32 v3, v2, 6, v3
	v_lshlrev_b32_e32 v186, 2, v2
	v_cmp_gt_u32_e32 vcc, 2, v0
	v_lshl_add_u32 v189, v2, 4, s12
	v_lshlrev_b32_e32 v0, 5, v0
	v_and_b32_e32 v2, 1, v10
	v_lshl_add_u64 v[170:171], s[2:3], 0, v[0:1]
	v_add3_u32 v0, v12, v13, v15
	v_lshlrev_b32_e32 v2, 6, v2
	v_lshl_or_b32 v0, v0, 11, v2
	v_lshl_add_u32 v0, v11, 1, v0
	s_mov_b64 s[38:39], 0x40080
	v_and_b32_e32 v2, 1, v14
	v_lshl_add_u64 v[172:173], v[0:1], 0, s[38:39]
	v_add3_u32 v0, v17, v18, v19
	v_lshlrev_b32_e32 v2, 6, v2
	v_and_b32_e32 v4, 32, v186
	s_waitcnt vmcnt(6)
	v_lshl_or_b32 v0, v0, 11, v2
	v_bitop3_b32 v5, v3, s8, v4 bitop3:0xde
	v_or_b32_e32 v188, s13, v146
	v_or_b32_e32 v154, 4, v146
	v_or_b32_e32 v156, 5, v146
	v_or_b32_e32 v166, 6, v146
	v_or_b32_e32 v168, 7, v146
	v_lshl_add_u32 v0, v16, 1, v0
	s_lshl_b32 s76, s13, 1
	v_readlane_b32 s12, v253, 25
	v_bitop3_b32 v187, v3, s9, v4 bitop3:0xde
	v_mov_b32_e32 v147, v1
	s_mov_b32 s75, 0
	s_and_b64 s[36:37], s[4:5], vcc
	v_or_b32_e32 v148, 1, v146
	v_mov_b32_e32 v149, v1
	v_or_b32_e32 v150, 2, v146
	v_mov_b32_e32 v151, v1
	v_or_b32_e32 v152, 3, v146
	v_mov_b32_e32 v153, v1
	v_cmp_gt_u32_e64 s[4:5], 12, v154
	v_mov_b32_e32 v155, v1
	v_cmp_gt_u32_e64 s[6:7], 12, v156
	v_mov_b32_e32 v157, v1
	v_cmp_gt_u32_e64 s[8:9], 12, v166
	v_mov_b32_e32 v167, v1
	v_cmp_gt_u32_e64 s[10:11], 12, v168
	v_mov_b32_e32 v169, v1
	v_lshl_add_u64 v[174:175], v[0:1], 0, s[38:39]
	s_mov_b64 s[38:39], -1
	s_mov_b64 s[40:41], 0
	v_add_u32_e32 v190, 0, v5
	v_readlane_b32 s57, v253, 14
	s_mov_b32 s56, s12
	s_mov_b32 s97, s81
	s_barrier
	v_readlane_b32 s13, v253, 26
	s_branch .LBB0_213

.LBB0_319:
	s_and_b32 s5, s5, 3
	s_add_i32 m0, s62, 0x18000
	v_lshl_add_u64 v[8:9], v[8:9], 0, s[82:83]
	s_lshl_b32 s66, s12, 6
	s_lshl_b32 s8, s12, 13
	s_lshl_b32 s13, s5, 5
	s_lshl_b32 s9, s5, 12
	global_load_lds_dwordx4 v[8:9], off
	v_lshl_add_u64 v[6:7], v[6:7], 0, s[82:83]
	s_add_i32 m0, s62, 0x1a000
	s_add_i32 s67, s62, 0x8000
	s_add_i32 s68, s62, 0xa000
	global_load_lds_dwordx4 v[6:7], off
	v_lshl_add_u64 v[2:3], v[2:3], 0, s[82:83]
	s_mov_b32 m0, s67
	s_add_u32 s6, s48, 0x40080
	global_load_lds_dwordx4 v[2:3], off
	v_lshl_add_u64 v[2:3], v[4:5], 0, s[82:83]
	s_mov_b32 m0, s68
	s_addc_u32 s7, s49, 0
	global_load_lds_dwordx4 v[2:3], off
	s_add_i32 m0, s62, 0x1c000
	v_lshl_add_u64 v[2:3], s[6:7], 0, v[140:141]
	global_load_lds_dwordx4 v[2:3], off
	v_lshl_add_u64 v[2:3], s[6:7], 0, v[144:145]
	s_add_i32 m0, s62, 0x1e000
	s_cmpk_lt_u32 s4, 0x100
	global_load_lds_dwordx4 v[2:3], off
	s_waitcnt vmcnt(8)
	s_barrier
	s_cselect_b64 s[34:35], -1, 0
	s_cmp_eq_u32 s5, 0
	s_cselect_b64 s[4:5], -1, 0
	s_lshl_b32 s12, s12, 8
	v_and_b32_e32 v2, 15, v0
	v_bfe_u32 v0, v0, 4, 2
	s_add_i32 s12, s12, 0
	v_lshlrev_b32_e32 v3, 4, v0
	s_add_i32 s12, s12, 0x20400
	v_lshlrev_b32_e32 v146, 3, v0
	v_lshl_or_b32 v3, v2, 6, v3
	v_lshlrev_b32_e32 v186, 2, v2
	v_cmp_gt_u32_e32 vcc, 2, v0
	v_lshl_add_u32 v189, v2, 4, s12
	v_lshlrev_b32_e32 v0, 5, v0
	v_and_b32_e32 v2, 1, v10
	v_lshl_add_u64 v[170:171], s[2:3], 0, v[0:1]
	v_add3_u32 v0, v12, v13, v15
	v_lshlrev_b32_e32 v2, 6, v2
	v_lshl_or_b32 v0, v0, 11, v2
	v_lshl_add_u32 v0, v11, 1, v0
	s_mov_b64 s[2:3], 0x40080
	v_and_b32_e32 v2, 1, v14
	v_lshl_add_u64 v[172:173], v[0:1], 0, s[2:3]
	v_add3_u32 v0, v17, v18, v19
	v_lshlrev_b32_e32 v2, 6, v2
	v_and_b32_e32 v4, 32, v186
	s_waitcnt vmcnt(6)
	v_lshl_or_b32 v0, v0, 11, v2
	v_bitop3_b32 v5, v3, s8, v4 bitop3:0xde
	v_or_b32_e32 v188, s13, v146
	v_or_b32_e32 v154, 4, v146
	v_or_b32_e32 v156, 5, v146
	v_or_b32_e32 v166, 6, v146
	v_or_b32_e32 v168, 7, v146
	v_lshl_add_u32 v0, v16, 1, v0
	s_lshl_b32 s70, s13, 1
	v_readlane_b32 s12, v253, 33
	v_bitop3_b32 v187, v3, s9, v4 bitop3:0xde
	v_mov_b32_e32 v147, v1
	s_mov_b32 s69, 0
	s_and_b64 s[36:37], s[4:5], vcc
	v_or_b32_e32 v148, 1, v146
	v_mov_b32_e32 v149, v1
	v_or_b32_e32 v150, 2, v146
	v_mov_b32_e32 v151, v1
	v_or_b32_e32 v152, 3, v146
	v_mov_b32_e32 v153, v1
	v_cmp_gt_u32_e64 s[4:5], 12, v154
	v_mov_b32_e32 v155, v1
	v_cmp_gt_u32_e64 s[6:7], 12, v156
	v_mov_b32_e32 v157, v1
	v_cmp_gt_u32_e64 s[8:9], 12, v166
	v_mov_b32_e32 v167, v1
	v_cmp_gt_u32_e64 s[10:11], 12, v168
	v_mov_b32_e32 v169, v1
	v_lshl_add_u64 v[174:175], v[0:1], 0, s[2:3]
	s_mov_b64 s[2:3], -1
	s_mov_b64 s[38:39], 0
	v_add_u32_e32 v190, 0, v5
	v_readlane_b32 s55, v253, 15
	s_mov_b32 s54, s12
	s_barrier
	v_readlane_b32 s13, v253, 34
	s_branch .LBB0_322

.LBB0_429:
	s_and_b32 s7, s7, 3
	s_add_i32 m0, s36, 0x18000
	v_lshl_add_u64 v[8:9], v[8:9], 0, s[82:83]
	s_lshl_b32 s40, s8, 6
	s_lshl_b32 s9, s8, 13
	s_lshl_b32 s12, s7, 5
	s_lshl_b32 s7, s7, 12
	global_load_lds_dwordx4 v[8:9], off
	v_lshl_add_u64 v[6:7], v[6:7], 0, s[82:83]
	s_add_i32 m0, s36, 0x1a000
	s_add_i32 s41, s36, 0x8000
	s_add_i32 s42, s36, 0xa000
	global_load_lds_dwordx4 v[6:7], off
	v_lshl_add_u64 v[2:3], v[2:3], 0, s[82:83]
	s_mov_b32 m0, s41
	s_add_u32 s10, s22, 0x40080
	global_load_lds_dwordx4 v[2:3], off
	v_lshl_add_u64 v[2:3], v[4:5], 0, s[82:83]
	s_mov_b32 m0, s42
	s_addc_u32 s11, s23, 0
	global_load_lds_dwordx4 v[2:3], off
	s_add_i32 m0, s36, 0x1c000
	v_lshl_add_u64 v[2:3], s[10:11], 0, v[132:133]
	global_load_lds_dwordx4 v[2:3], off
	v_lshl_add_u64 v[2:3], s[10:11], 0, v[136:137]
	s_add_i32 m0, s36, 0x1e000
	s_cmpk_lt_u32 s6, 0x100
	global_load_lds_dwordx4 v[2:3], off
	s_waitcnt vmcnt(8)
	s_barrier
	v_and_b32_e32 v3, 15, v0
	v_bfe_u32 v0, v0, 4, 2
	v_lshlrev_b32_e32 v2, 3, v0
	v_lshlrev_b32_e32 v0, 4, v0
	v_lshlrev_b32_e32 v171, 2, v3
	v_lshl_or_b32 v0, v3, 6, v0
	v_and_b32_e32 v4, 32, v171
	v_bitop3_b32 v173, v0, s7, v4 bitop3:0xde
	s_cselect_b64 s[6:7], -1, 0
	s_lshl_b32 s8, s8, 8
	s_add_i32 s8, s8, 0
	s_add_i32 s8, s8, 0x20400
	v_bitop3_b32 v5, v0, s9, v4 bitop3:0xde
	v_lshl_add_u32 v175, v3, 4, s8
	v_readlane_b32 s8, v253, 54
	v_or_b32_e32 v0, s12, v2
	v_readlane_b32 s9, v253, 55
	v_and_b32_e32 v3, 1, v10
	v_lshlrev_b32_e32 v4, 8, v0
	s_lshl_b64 s[8:9], s[8:9], 1
	v_add3_u32 v0, v12, v13, v15
	v_lshlrev_b32_e32 v3, 6, v3
	s_add_u32 s43, s16, s8
	v_lshl_or_b32 v0, v0, 11, v3
	s_addc_u32 s44, s17, s9
	v_lshl_add_u32 v0, v11, 1, v0
	s_mov_b64 s[8:9], 0x40080
	v_and_b32_e32 v3, 1, v14
	v_lshl_add_u64 v[138:139], v[0:1], 0, s[8:9]
	v_add3_u32 v0, v17, v18, v19
	v_lshlrev_b32_e32 v3, 6, v3
	s_waitcnt vmcnt(6)
	v_lshl_or_b32 v0, v0, 11, v3
	v_or_b32_e32 v6, 0x8000, v4
	v_or_b32_e32 v8, 0x8100, v4
	v_or_b32_e32 v20, 0x8200, v4
	v_or_b32_e32 v22, 0x8300, v4
	v_or_b32_e32 v24, 0x8400, v4
	v_or_b32_e32 v26, 0x8500, v4
	v_or_b32_e32 v28, 0x8600, v4
	v_or_b32_e32 v30, 0x8700, v4
	v_lshl_add_u32 v0, v16, 1, v0
	v_lshl_add_u64 v[140:141], v[0:1], 0, s[8:9]
	s_mov_b32 s45, 0
	s_mov_b64 s[8:9], -1
	s_mov_b64 s[10:11], 0
	v_add_u32_e32 v177, 0, v5
	v_lshlrev_b32_e32 v142, 1, v4
	v_lshlrev_b32_e32 v144, 1, v6
	v_lshlrev_b32_e32 v146, 1, v8
	v_lshlrev_b32_e32 v148, 1, v20
	v_lshlrev_b32_e32 v150, 1, v22
	v_lshlrev_b32_e32 v152, 1, v24
	v_lshlrev_b32_e32 v154, 1, v26
	v_lshlrev_b32_e32 v156, 1, v28
	v_lshlrev_b32_e32 v166, 1, v30
	s_lshl_b32 s46, s12, 1
	v_lshlrev_b32_e32 v168, 1, v2
	v_readlane_b32 s47, v253, 58
	v_readlane_b32 s48, v253, 60
	s_barrier
	s_branch .LBB0_432

.LBB0_683:
	s_add_u32 s8, s4, 0x4500000
	s_addc_u32 s9, s5, 0
	s_lshl_b64 s[10:11], s[80:81], 2
	s_add_u32 s4, s4, s10
	s_addc_u32 s5, s5, s11
	v_bfe_u32 v17, v16, 4, 2
	s_add_u32 s10, s4, 0x3220000
	v_and_b32_e32 v18, 15, v16
	v_lshlrev_b32_e32 v19, 4, v17
	v_lshlrev_b32_e32 v16, 2, v16
	s_addc_u32 s11, s5, 0
	v_lshl_or_b32 v190, s12, 6, v18
	v_lshl_or_b32 v18, v18, 6, v19
	s_lshl_b32 s4, s12, 13
	v_and_b32_e32 v16, 32, v16
	v_bitop3_b32 v19, v18, s4, v16 bitop3:0xde
	s_lshl_b32 s4, s7, 5
	s_and_b32 s7, s4, 0x60
	s_add_i32 m0, s34, 0x18000
	v_lshl_add_u64 v[8:9], v[8:9], 0, s[82:83]
	s_lshl_b32 s4, s7, 7
	global_load_lds_dwordx4 v[8:9], off
	v_lshl_add_u64 v[6:7], v[6:7], 0, s[82:83]
	s_add_i32 m0, s34, 0x1a000
	s_add_i32 s38, s34, 0x8000
	s_add_i32 s39, s34, 0xa000
	v_bitop3_b32 v191, v18, s4, v16 bitop3:0xde
	global_load_lds_dwordx4 v[6:7], off
	v_lshl_add_u64 v[2:3], v[2:3], 0, s[82:83]
	s_mov_b32 m0, s38
	s_add_u32 s4, s24, 0x40080
	global_load_lds_dwordx4 v[2:3], off
	v_lshl_add_u64 v[2:3], v[4:5], 0, s[82:83]
	s_mov_b32 m0, s39
	s_addc_u32 s5, s25, 0
	global_load_lds_dwordx4 v[2:3], off
	s_add_i32 m0, s34, 0x1c000
	v_lshl_add_u64 v[2:3], s[4:5], 0, v[0:1]
	global_load_lds_dwordx4 v[2:3], off
	v_lshl_add_u64 v[2:3], s[4:5], 0, v[154:155]
	s_add_i32 m0, s34, 0x1e000
	s_cmpk_lt_u32 s6, 0x100
	global_load_lds_dwordx4 v[2:3], off
	s_waitcnt vmcnt(8)
	s_barrier
	v_lshlrev_b32_e32 v2, 14, v14
	v_and_b32_e32 v2, 0xffff8000, v2
	v_lshl_add_u32 v2, v13, 11, v2
	v_and_b32_e32 v3, 1, v14
	v_lshl_or_b32 v2, v3, 6, v2
	v_lshl_add_u32 v168, v15, 1, v2
	v_lshlrev_b32_e32 v2, 14, v10
	v_and_b32_e32 v2, 0xffff8000, v2
	s_waitcnt vmcnt(6)
	v_lshl_add_u32 v2, v11, 11, v2
	v_and_b32_e32 v3, 1, v10
	v_lshl_or_b32 v192, v17, 3, s7
	v_lshl_or_b32 v2, v3, 6, v2
	v_readlane_b32 s6, v253, 37
	s_cselect_b64 s[12:13], -1, 0
	s_mov_b32 s40, 0
	v_cmp_eq_u32_e64 s[4:5], 0, v17
	v_mov_b32_e32 v169, v1
	v_lshl_add_u32 v170, v12, 1, v2
	v_mov_b32_e32 v171, v1
	v_add_u32_e32 v193, 0, v19
	v_readlane_b32 s41, v253, 20
	s_mov_b32 s42, s6
	s_barrier
	v_readlane_b32 s7, v253, 38
	s_branch .LBB0_686

.LBB0_776:
	s_add_u32 s14, s4, 0x8500000
	v_and_b32_e32 v225, 15, v10
	v_lshrrev_b32_e32 v10, 1, v10
	s_addc_u32 s15, s5, 0
	v_and_b32_e32 v226, 24, v10
	s_add_u32 s16, s4, 0xb100000
	v_lshlrev_b32_e32 v10, 1, v226
	v_lshlrev_b32_e32 v227, 2, v225
	s_addc_u32 s17, s5, 0
	v_lshl_or_b32 v10, v225, 6, v10
	s_lshl_b32 s4, s7, 13
	v_and_b32_e32 v20, 32, v227
	v_bitop3_b32 v21, v10, s4, v20 bitop3:0xde
	s_lshl_b32 s4, s18, 5
	s_and_b32 s57, s4, 0x60
	s_add_i32 m0, s52, 0x18000
	v_lshl_add_u64 v[8:9], v[8:9], 0, s[82:83]
	s_lshl_b32 s56, s7, 6
	s_lshl_b32 s4, s57, 7
	global_load_lds_dwordx4 v[8:9], off
	v_lshl_add_u64 v[6:7], v[6:7], 0, s[82:83]
	s_add_i32 m0, s52, 0x1a000
	s_add_i32 s58, s52, 0x8000
	s_add_i32 s59, s52, 0xa000
	v_bitop3_b32 v228, v10, s4, v20 bitop3:0xde
	global_load_lds_dwordx4 v[6:7], off
	v_lshl_add_u64 v[2:3], v[2:3], 0, s[82:83]
	s_mov_b32 m0, s58
	s_add_u32 s4, s10, 0x40080
	global_load_lds_dwordx4 v[2:3], off
	v_lshl_add_u64 v[2:3], v[4:5], 0, s[82:83]
	s_mov_b32 m0, s59
	s_addc_u32 s5, s11, 0
	global_load_lds_dwordx4 v[2:3], off
	s_add_i32 m0, s52, 0x1c000
	v_lshl_add_u64 v[2:3], s[4:5], 0, v[144:145]
	global_load_lds_dwordx4 v[2:3], off
	v_lshl_add_u64 v[2:3], s[4:5], 0, v[148:149]
	s_add_i32 m0, s52, 0x1e000
	v_and_b32_e32 v0, 1, v0
	global_load_lds_dwordx4 v[2:3], off
	s_waitcnt vmcnt(8)
	s_barrier
	v_add3_u32 v2, v12, v13, v15
	v_lshlrev_b32_e32 v0, 6, v0
	s_cmpk_lt_u32 s6, 0x100
	v_lshl_or_b32 v0, v2, 11, v0
	s_cselect_b64 s[18:19], -1, 0
	s_lshl_b32 s61, s7, 2
	v_lshl_add_u32 v0, v11, 1, v0
	s_mov_b64 s[6:7], 0x40080
	v_and_b32_e32 v2, 1, v14
	v_lshl_add_u64 v[150:151], v[0:1], 0, s[6:7]
	v_add3_u32 v0, v17, v18, v19
	v_lshlrev_b32_e32 v2, 6, v2
	v_lshl_or_b32 v0, v0, 11, v2
	s_waitcnt vmcnt(6)
	v_cmp_eq_u32_e64 s[4:5], 0, v225
	v_lshl_add_u32 v0, v16, 1, v0
	v_lshl_add_u64 v[152:153], v[0:1], 0, s[6:7]
	v_cndmask_b32_e64 v230, 2, 0, s[4:5]
	v_readlane_b32 s6, v253, 47
	v_or_b32_e32 v229, s56, v227
	s_mov_b32 s60, 0
	v_or_b32_e32 v231, 8, v230
	v_or_b32_e32 v232, s57, v226
	s_mov_b64 s[20:21], -1
	s_mov_b64 s[22:23], 0
	v_add_u32_e32 v233, 0, v21
	v_readlane_b32 s63, v253, 51
	s_mov_b32 s62, s6
	s_barrier
	v_readlane_b32 s7, v253, 48
	s_branch .LBB0_779

.LBB0_952:
	s_add_u32 s10, s4, 0x4500000
	s_addc_u32 s11, s5, 0
	s_lshl_b64 s[12:13], s[80:81], 2
	s_add_u32 s4, s4, s12
	s_addc_u32 s5, s5, s13
	v_bfe_u32 v19, v18, 4, 2
	s_add_u32 s12, s4, 0x3240000
	v_and_b32_e32 v20, 15, v18
	v_lshlrev_b32_e32 v21, 4, v19
	v_lshlrev_b32_e32 v18, 2, v18
	s_addc_u32 s13, s5, 0
	v_lshl_or_b32 v190, s8, 6, v20
	v_lshl_or_b32 v20, v20, 6, v21
	s_lshl_b32 s4, s8, 13
	v_and_b32_e32 v18, 32, v18
	v_bitop3_b32 v21, v20, s4, v18 bitop3:0xde
	s_lshl_b32 s4, s7, 5
	s_and_b32 s7, s4, 0x60
	s_add_i32 m0, s31, 0x18000
	v_lshl_add_u64 v[8:9], v[8:9], 0, s[82:83]
	s_lshl_b32 s4, s7, 7
	global_load_lds_dwordx4 v[8:9], off
	v_lshl_add_u64 v[6:7], v[6:7], 0, s[82:83]
	s_add_i32 m0, s31, 0x1a000
	s_add_i32 s36, s31, 0x8000
	s_add_i32 s37, s31, 0xa000
	v_bitop3_b32 v191, v20, s4, v18 bitop3:0xde
	global_load_lds_dwordx4 v[6:7], off
	v_lshl_add_u64 v[2:3], v[2:3], 0, s[82:83]
	s_mov_b32 m0, s36
	s_add_u32 s4, s20, 0xb0080
	global_load_lds_dwordx4 v[2:3], off
	v_lshl_add_u64 v[2:3], v[4:5], 0, s[82:83]
	s_mov_b32 m0, s37
	s_addc_u32 s5, s21, 0
	global_load_lds_dwordx4 v[2:3], off
	s_add_i32 m0, s31, 0x1c000
	v_lshl_add_u64 v[2:3], s[4:5], 0, v[0:1]
	global_load_lds_dwordx4 v[2:3], off
	v_lshl_add_u64 v[2:3], s[4:5], 0, v[154:155]
	s_add_i32 m0, s31, 0x1e000
	s_movk_i32 s8, 0xb00
	global_load_lds_dwordx4 v[2:3], off
	s_waitcnt vmcnt(8)
	s_barrier
	v_lshrrev_b32_e32 v3, 1, v15
	v_mul_lo_u32 v2, v14, s8
	s_mov_b32 s9, 0xb000
	s_cmpk_lt_u32 s6, 0x100
	v_lshl_or_b32 v192, v19, 3, s7
	v_mad_u64_u32 v[2:3], s[6:7], v3, s9, v[2:3]
	v_or_b32_e32 v2, v2, v16
	v_add_lshl_u32 v2, v2, v17, 1
	v_mov_b32_e32 v3, v1
	s_mov_b64 s[16:17], 0xb0080
	v_lshl_add_u64 v[168:169], v[2:3], 0, s[16:17]
	v_lshrrev_b32_e32 v3, 1, v10
	v_mul_lo_u32 v2, v11, s8
	v_mad_u64_u32 v[2:3], s[6:7], v3, s9, v[2:3]
	s_waitcnt vmcnt(6)
	v_or_b32_e32 v2, v2, v12
	v_add_lshl_u32 v2, v2, v13, 1
	v_mov_b32_e32 v3, v1
	v_readlane_b32 s6, v253, 37
	s_cselect_b64 s[14:15], -1, 0
	s_mov_b32 s38, 0
	v_cmp_eq_u32_e64 s[4:5], 0, v19
	v_lshl_add_u64 v[170:171], v[2:3], 0, s[16:17]
	v_add_u32_e32 v193, 0, v21
	v_readlane_b32 s41, v253, 20
	s_mov_b32 s42, s6
	s_barrier
	v_readlane_b32 s7, v253, 38
	s_branch .LBB0_955
